# K-loop: pointer bumps, loop test and prefetch address math moved from the end of MFMA segments to after the barriers
# baseline (speedup 1.0000x reference)
; #define PG8_STAGE(bufoff, gbase, voff) do { _Pragma("unroll") for (int _i = 0; _i < 2; ++_i) \
;         __builtin_amdgcn_global_load_lds((const unsigned*)((const char*)(gbase) + (voff)[_i]), (LAS unsigned*)(lds + (bufoff) + ldsw + _i * 8192), 16, 0, 0); } while (0)
; #define PG8_LDA(dst, b, h) do { _Pragma("unroll") for (int m = 0; m < 4; ++m) _Pragma("unroll") for (int k = 0; k < 2; ++k) dst[m][k] = *(const LAS bf16x8*)(lds + PG8_SA(b, h) + aoff + m * 2048 + k * 1024); } while (0)
; #define PG8_LDB(dst, b, h) do { _Pragma("unroll") for (int n = 0; n < 2; ++n) _Pragma("unroll") for (int k = 0; k < 2; ++k) dst[n][k] = *(const LAS bf16x8*)(lds + PG8_SB(b, h) + boff + n * 2048 + k * 1024); } while (0)
; #define PG8_MMA(ai, bj, At, Bt) do { __builtin_amdgcn_s_setprio(1); _Pragma("unroll") for (int m = 0; m < 4; ++m) _Pragma("unroll") for (int n = 0; n < 2; ++n) _Pragma("unroll") for (int k = 0; k < 2; ++k) \
;         acc[ai][bj][m][n] = __builtin_amdgcn_mfma_f32_16x16x32_bf16(Bt[n][k], At[m][k], acc[ai][bj][m][n], 0, 0, 0); __builtin_amdgcn_s_setprio(0); } while (0)
; #define PG8_WAIT_L(n) asm volatile("s_waitcnt lgkmcnt(" #n ")" ::: "memory")
; #define PG8_BAR __builtin_amdgcn_s_barrier()
; #define PG8_SCHED __builtin_amdgcn_sched_barrier(0)
; template <class EpiFn>
; DI void gemm_phase(LAS unsigned char* lds, const Sched& S, const bool perm, const EpiFn& E) {
;     ...
;             PG8_LDB(B0, 0, 0); PG8_SCHED; PG8_LDA(At, 0, 0); PG8_STAGE(PG8_SA(1, 1), a1 + hstep, voffA);
;             PG8_WAIT_L(8); PG8_BAR; PG8_WAIT_L(0); PG8_MMA(0, 0, At, B0); PG8_BAR; PG8_SCHED;
;             PG8_LDB(B1, 0, 1); PG8_STAGE(PG8_SB(0, 0), b2, voffB);
;             PG8_BAR; PG8_WAIT_L(0); PG8_MMA(0, 1, At, B1); PG8_BAR;
;             PG8_LDA(At, 0, 1); PG8_STAGE(PG8_SA(0, 0), a2, voffA);
;             PG8_BAR; PG8_WAIT_L(0); PG8_MMA(1, 0, At, B0); PG8_BAR; PG8_SCHED;
.LBB0_394:
	s_cmp_lg_u32 s43, 0
	s_cselect_b64 s[28:29], -1, 0
	s_cmp_eq_u32 s43, 0
	s_cselect_b32 s16, s24, s86
	s_add_i32 s17, s16, -2
	s_add_u32 s6, s40, 0x80
	s_addc_u32 s7, s41, 0
	s_add_u32 s18, s8, 0x100
	s_mov_b32 s60, 0
	s_addc_u32 s51, s9, 0
	s_add_i32 s61, s60, 2
	s_add_u32 s8, s6, 0x80
	s_addc_u32 s9, s7, 0
	s_add_i32 s62, 0, 0x10000
	v_add_u32_e32 v0, s62, v222
	ds_read_b128 v[130:133], v0
	ds_read_b128 v[134:137], v0 offset:1024
	ds_read_b128 v[138:141], v0 offset:2048
	ds_read_b128 v[142:145], v0 offset:3072
	s_cmp_eq_u32 s17, s60
	s_cselect_b32 s9, s13, s9
	s_cselect_b32 s8, s12, s8
	s_cselect_b32 s41, s39, s51
	s_cselect_b32 s40, s38, s18
	v_lshl_add_u64 v[178:179], s[6:7], 0, v[196:197]
	s_add_i32 m0, s26, 0xc000
	ds_read_b128 v[146:149], v228
	ds_read_b128 v[150:153], v228 offset:1024
	ds_read_b128 v[154:157], v228 offset:2048
	ds_read_b128 v[158:161], v228 offset:3072
	ds_read_b128 v[162:165], v228 offset:4096
	ds_read_b128 v[166:169], v228 offset:5120
	ds_read_b128 v[170:173], v228 offset:6144
	ds_read_b128 v[174:177], v228 offset:7168
	global_load_lds_dwordx4 v[178:179], off
	v_lshl_add_u64 v[178:179], s[6:7], 0, v[198:199]
	s_add_i32 m0, s26, 0xe000
	s_nop 0
	global_load_lds_dwordx4 v[178:179], off
	s_waitcnt lgkmcnt(8)
	s_barrier
	s_waitcnt lgkmcnt(0)
	s_setprio 1
	s_waitcnt lgkmcnt(0)
	v_mfma_f32_16x16x32_bf16 v[118:121], v[130:133], v[146:149], 0
	v_mfma_f32_16x16x32_bf16 v[106:109], v[138:141], v[146:149], 0
	v_mfma_f32_16x16x32_bf16 v[50:53], v[130:133], v[154:157], 0
	v_mfma_f32_16x16x32_bf16 v[42:45], v[138:141], v[154:157], 0
	v_mfma_f32_16x16x32_bf16 v[30:33], v[130:133], v[162:165], 0
	v_mfma_f32_16x16x32_bf16 v[26:29], v[138:141], v[162:165], 0
	v_mfma_f32_16x16x32_bf16 v[14:17], v[130:133], v[170:173], 0
	v_mfma_f32_16x16x32_bf16 v[10:13], v[138:141], v[170:173], 0
	v_mfma_f32_16x16x32_bf16 v[118:121], v[134:137], v[150:153], v[118:121]
	v_mfma_f32_16x16x32_bf16 v[106:109], v[142:145], v[150:153], v[106:109]
	v_mfma_f32_16x16x32_bf16 v[50:53], v[134:137], v[158:161], v[50:53]
	v_mfma_f32_16x16x32_bf16 v[42:45], v[142:145], v[158:161], v[42:45]
	v_mfma_f32_16x16x32_bf16 v[30:33], v[134:137], v[166:169], v[30:33]
	v_mfma_f32_16x16x32_bf16 v[26:29], v[142:145], v[166:169], v[26:29]
	v_mfma_f32_16x16x32_bf16 v[14:17], v[134:137], v[174:177], v[14:17]
	v_mfma_f32_16x16x32_bf16 v[10:13], v[142:145], v[174:177], v[10:13]
	s_setprio 0
	s_barrier
	s_add_i32 s60, 0, 0x14000
	s_add_i32 s62, s62, s75
	v_add_u32_e32 v0, s60, v222
	v_lshl_add_u64 v[208:209], s[40:41], 0, v[192:193]
	s_mov_b32 m0, s62
	ds_read_b128 v[178:181], v0
	ds_read_b128 v[182:185], v0 offset:1024
	ds_read_b128 v[200:203], v0 offset:2048
	ds_read_b128 v[204:207], v0 offset:3072
	global_load_lds_dwordx4 v[208:209], off
	v_lshl_add_u64 v[230:231], s[40:41], 0, v[188:189]
	s_add_i32 m0, s62, 0x2000
	s_nop 0
	global_load_lds_dwordx4 v[230:231], off
	s_barrier
	s_waitcnt lgkmcnt(0)
	s_setprio 1
	s_waitcnt lgkmcnt(0)
	v_mfma_f32_16x16x32_bf16 v[70:73], v[178:181], v[146:149], 0
	v_mfma_f32_16x16x32_bf16 v[58:61], v[200:203], v[146:149], 0
	v_mfma_f32_16x16x32_bf16 v[38:41], v[178:181], v[154:157], 0
	v_mfma_f32_16x16x32_bf16 v[34:37], v[200:203], v[154:157], 0
	v_mfma_f32_16x16x32_bf16 v[22:25], v[178:181], v[162:165], 0
	v_mfma_f32_16x16x32_bf16 v[18:21], v[200:203], v[162:165], 0
	v_mfma_f32_16x16x32_bf16 v[6:9], v[178:181], v[170:173], 0
	v_mfma_f32_16x16x32_bf16 v[2:5], v[200:203], v[170:173], 0
	v_mfma_f32_16x16x32_bf16 v[70:73], v[182:185], v[150:153], v[70:73]
	v_mfma_f32_16x16x32_bf16 v[58:61], v[204:207], v[150:153], v[58:61]
	v_mfma_f32_16x16x32_bf16 v[38:41], v[182:185], v[158:161], v[38:41]
	v_mfma_f32_16x16x32_bf16 v[34:37], v[204:207], v[158:161], v[34:37]
	v_mfma_f32_16x16x32_bf16 v[22:25], v[182:185], v[166:169], v[22:25]
	v_mfma_f32_16x16x32_bf16 v[18:21], v[204:207], v[166:169], v[18:21]
	v_mfma_f32_16x16x32_bf16 v[6:9], v[182:185], v[174:177], v[6:9]
	v_mfma_f32_16x16x32_bf16 v[2:5], v[204:207], v[174:177], v[2:5]
	s_setprio 0
	s_barrier
	s_mov_b32 m0, s26
	v_lshl_add_u64 v[232:233], s[8:9], 0, v[190:191]
	ds_read_b128 v[146:149], v228 offset:16384
	ds_read_b128 v[150:153], v228 offset:17408
	ds_read_b128 v[154:157], v228 offset:18432
	ds_read_b128 v[158:161], v228 offset:19456
	ds_read_b128 v[162:165], v228 offset:20480
	ds_read_b128 v[166:169], v228 offset:21504
	ds_read_b128 v[170:173], v228 offset:22528
	ds_read_b128 v[174:177], v228 offset:23552
	global_load_lds_dwordx4 v[232:233], off
	v_lshl_add_u64 v[234:235], s[8:9], 0, v[186:187]
	s_mov_b32 m0, s57
	s_nop 0
	global_load_lds_dwordx4 v[234:235], off
	s_barrier
	s_waitcnt lgkmcnt(0)
	s_setprio 1
	s_waitcnt lgkmcnt(0)
	v_mfma_f32_16x16x32_bf16 v[126:129], v[130:133], v[146:149], 0
	v_mfma_f32_16x16x32_bf16 v[122:125], v[138:141], v[146:149], 0
	v_mfma_f32_16x16x32_bf16 v[114:117], v[130:133], v[154:157], 0
	v_mfma_f32_16x16x32_bf16 v[110:113], v[138:141], v[154:157], 0
	v_mfma_f32_16x16x32_bf16 v[98:101], v[130:133], v[162:165], 0
	v_mfma_f32_16x16x32_bf16 v[90:93], v[138:141], v[162:165], 0
	v_mfma_f32_16x16x32_bf16 v[82:85], v[130:133], v[170:173], 0
	v_mfma_f32_16x16x32_bf16 v[74:77], v[138:141], v[170:173], 0
	v_mfma_f32_16x16x32_bf16 v[126:129], v[134:137], v[150:153], v[126:129]
	v_mfma_f32_16x16x32_bf16 v[122:125], v[142:145], v[150:153], v[122:125]
	v_mfma_f32_16x16x32_bf16 v[114:117], v[134:137], v[158:161], v[114:117]
	v_mfma_f32_16x16x32_bf16 v[110:113], v[142:145], v[158:161], v[110:113]
	v_mfma_f32_16x16x32_bf16 v[98:101], v[134:137], v[166:169], v[98:101]
	v_mfma_f32_16x16x32_bf16 v[90:93], v[142:145], v[166:169], v[90:93]
	v_mfma_f32_16x16x32_bf16 v[82:85], v[134:137], v[174:177], v[82:85]
	v_mfma_f32_16x16x32_bf16 v[74:77], v[142:145], v[174:177], v[74:77]
	s_setprio 0
	s_barrier
; #define PG8_STAGE(bufoff, gbase, voff) do { _Pragma("unroll") for (int _i = 0; _i < 2; ++_i) \
;         __builtin_amdgcn_global_load_lds((const unsigned*)((const char*)(gbase) + (voff)[_i]), (LAS unsigned*)(lds + (bufoff) + ldsw + _i * 8192), 16, 0, 0); } while (0)
; #define PG8_LDA(dst, b, h) do { _Pragma("unroll") for (int m = 0; m < 4; ++m) _Pragma("unroll") for (int k = 0; k < 2; ++k) dst[m][k] = *(const LAS bf16x8*)(lds + PG8_SA(b, h) + aoff + m * 2048 + k * 1024); } while (0)
; #define PG8_LDB(dst, b, h) do { _Pragma("unroll") for (int n = 0; n < 2; ++n) _Pragma("unroll") for (int k = 0; k < 2; ++k) dst[n][k] = *(const LAS bf16x8*)(lds + PG8_SB(b, h) + boff + n * 2048 + k * 1024); } while (0)
; #define PG8_MMA(ai, bj, At, Bt) do { __builtin_amdgcn_s_setprio(1); _Pragma("unroll") for (int m = 0; m < 4; ++m) _Pragma("unroll") for (int n = 0; n < 2; ++n) _Pragma("unroll") for (int k = 0; k < 2; ++k) \
;         acc[ai][bj][m][n] = __builtin_amdgcn_mfma_f32_16x16x32_bf16(Bt[n][k], At[m][k], acc[ai][bj][m][n], 0, 0, 0); __builtin_amdgcn_s_setprio(0); } while (0)
; #define PG8_WAIT_V(n) asm volatile("s_waitcnt vmcnt(" #n ")" ::: "memory")
; #define PG8_WAIT_L(n) asm volatile("s_waitcnt lgkmcnt(" #n ")" ::: "memory")
; #define PG8_BAR __builtin_amdgcn_s_barrier()
; #define PG8_SCHED __builtin_amdgcn_sched_barrier(0)
; template <class EpiFn>
; DI void gemm_phase(LAS unsigned char* lds, const Sched& S, const bool perm, const EpiFn& E) {
;     ...
;             PG8_STAGE(PG8_SB(0, 1), b2 + hstep, voffB);
;             PG8_WAIT_V(6); PG8_BAR; PG8_MMA(1, 1, At, B1); PG8_BAR;
;             PG8_LDB(B0, 1, 0); PG8_SCHED; PG8_LDA(At, 1, 0); PG8_STAGE(PG8_SA(0, 1), a2 + hstep, voffA);
;             PG8_WAIT_L(8); PG8_BAR; PG8_WAIT_L(0); PG8_MMA(0, 0, At, B0); PG8_BAR; PG8_SCHED;
;             PG8_LDB(B1, 1, 1); PG8_STAGE(PG8_SB(1, 0), b3, voffB);
;             PG8_BAR; PG8_WAIT_L(0); PG8_MMA(0, 1, At, B1); PG8_BAR;
;             PG8_LDA(At, 1, 1); PG8_STAGE(PG8_SA(1, 0), a3, voffA);
	s_add_u32 s40, s40, s92
	s_addc_u32 s41, s41, s93
	s_add_i32 s60, s60, s75
	v_lshl_add_u64 v[236:237], s[40:41], 0, v[192:193]
	s_mov_b32 m0, s60
	v_lshl_add_u64 v[238:239], s[40:41], 0, v[188:189]
	global_load_lds_dwordx4 v[236:237], off
	s_add_i32 m0, s60, 0x2000
	s_nop 0
	global_load_lds_dwordx4 v[238:239], off
	s_waitcnt vmcnt(6)
	s_barrier
	s_setprio 1
	v_mfma_f32_16x16x32_bf16 v[102:105], v[178:181], v[146:149], 0
	v_mfma_f32_16x16x32_bf16 v[94:97], v[200:203], v[146:149], 0
	v_mfma_f32_16x16x32_bf16 v[86:89], v[178:181], v[154:157], 0
	v_mfma_f32_16x16x32_bf16 v[78:81], v[200:203], v[154:157], 0
	v_mfma_f32_16x16x32_bf16 v[66:69], v[178:181], v[162:165], 0
	v_mfma_f32_16x16x32_bf16 v[62:65], v[200:203], v[162:165], 0
	v_mfma_f32_16x16x32_bf16 v[54:57], v[178:181], v[170:173], 0
	v_mfma_f32_16x16x32_bf16 v[46:49], v[200:203], v[170:173], 0
	v_mfma_f32_16x16x32_bf16 v[102:105], v[182:185], v[150:153], v[102:105]
	v_mfma_f32_16x16x32_bf16 v[94:97], v[204:207], v[150:153], v[94:97]
	v_mfma_f32_16x16x32_bf16 v[86:89], v[182:185], v[158:161], v[86:89]
	v_mfma_f32_16x16x32_bf16 v[78:81], v[204:207], v[158:161], v[78:81]
	v_mfma_f32_16x16x32_bf16 v[66:69], v[182:185], v[166:169], v[66:69]
	v_mfma_f32_16x16x32_bf16 v[62:65], v[204:207], v[166:169], v[62:65]
	v_mfma_f32_16x16x32_bf16 v[54:57], v[182:185], v[174:177], v[54:57]
	v_mfma_f32_16x16x32_bf16 v[46:49], v[204:207], v[174:177], v[46:49]
	s_setprio 0
	s_barrier
	s_add_i32 s40, 0, 0x18000
	v_add_u32_e32 v0, s40, v222
	ds_read_b128 v[130:133], v0
	ds_read_b128 v[134:137], v0 offset:1024
	ds_read_b128 v[138:141], v0 offset:2048
	ds_read_b128 v[142:145], v0 offset:3072
	s_add_u32 s8, s8, s92
	s_addc_u32 s9, s9, s93
	s_mov_b32 m0, s54
	v_lshl_add_u64 v[178:179], s[8:9], 0, v[190:191]
	ds_read_b128 v[146:149], v228 offset:32768
	ds_read_b128 v[150:153], v228 offset:33792
	ds_read_b128 v[154:157], v228 offset:34816
	ds_read_b128 v[158:161], v228 offset:35840
	ds_read_b128 v[162:165], v228 offset:36864
	ds_read_b128 v[166:169], v228 offset:37888
	ds_read_b128 v[170:173], v228 offset:38912
	ds_read_b128 v[174:177], v228 offset:39936
	global_load_lds_dwordx4 v[178:179], off
	v_lshl_add_u64 v[178:179], s[8:9], 0, v[186:187]
	s_mov_b32 m0, s33
	s_nop 0
	global_load_lds_dwordx4 v[178:179], off
	s_waitcnt lgkmcnt(8)
	s_barrier
	s_waitcnt lgkmcnt(0)
	s_setprio 1
	s_waitcnt lgkmcnt(0)
	v_mfma_f32_16x16x32_bf16 v[118:121], v[130:133], v[146:149], v[118:121]
	v_mfma_f32_16x16x32_bf16 v[106:109], v[138:141], v[146:149], v[106:109]
	v_mfma_f32_16x16x32_bf16 v[50:53], v[130:133], v[154:157], v[50:53]
	v_mfma_f32_16x16x32_bf16 v[42:45], v[138:141], v[154:157], v[42:45]
	v_mfma_f32_16x16x32_bf16 v[30:33], v[130:133], v[162:165], v[30:33]
	v_mfma_f32_16x16x32_bf16 v[26:29], v[138:141], v[162:165], v[26:29]
	v_mfma_f32_16x16x32_bf16 v[14:17], v[130:133], v[170:173], v[14:17]
	v_mfma_f32_16x16x32_bf16 v[10:13], v[138:141], v[170:173], v[10:13]
	v_mfma_f32_16x16x32_bf16 v[118:121], v[134:137], v[150:153], v[118:121]
	v_mfma_f32_16x16x32_bf16 v[106:109], v[142:145], v[150:153], v[106:109]
	v_mfma_f32_16x16x32_bf16 v[50:53], v[134:137], v[158:161], v[50:53]
	v_mfma_f32_16x16x32_bf16 v[42:45], v[142:145], v[158:161], v[42:45]
	v_mfma_f32_16x16x32_bf16 v[30:33], v[134:137], v[166:169], v[30:33]
	v_mfma_f32_16x16x32_bf16 v[26:29], v[142:145], v[166:169], v[26:29]
	v_mfma_f32_16x16x32_bf16 v[14:17], v[134:137], v[174:177], v[14:17]
	v_mfma_f32_16x16x32_bf16 v[10:13], v[142:145], v[174:177], v[10:13]
	s_setprio 0
	s_barrier
	s_add_i32 s8, 0, 0x1c000
	s_add_i32 s9, s40, s75
	v_add_u32_e32 v0, s8, v222
	v_lshl_add_u64 v[208:209], v[208:209], 0, s[64:65]
	s_mov_b32 m0, s9
	ds_read_b128 v[178:181], v0
	ds_read_b128 v[182:185], v0 offset:1024
	ds_read_b128 v[200:203], v0 offset:2048
	ds_read_b128 v[204:207], v0 offset:3072
	global_load_lds_dwordx4 v[208:209], off
	v_lshl_add_u64 v[208:209], v[230:231], 0, s[64:65]
	s_add_i32 m0, s9, 0x2000
	s_nop 0
	global_load_lds_dwordx4 v[208:209], off
	s_barrier
	s_waitcnt lgkmcnt(0)
	s_setprio 1
	s_waitcnt lgkmcnt(0)
	v_mfma_f32_16x16x32_bf16 v[70:73], v[178:181], v[146:149], v[70:73]
	v_mfma_f32_16x16x32_bf16 v[58:61], v[200:203], v[146:149], v[58:61]
	v_mfma_f32_16x16x32_bf16 v[38:41], v[178:181], v[154:157], v[38:41]
	v_mfma_f32_16x16x32_bf16 v[34:37], v[200:203], v[154:157], v[34:37]
	v_mfma_f32_16x16x32_bf16 v[22:25], v[178:181], v[162:165], v[22:25]
	v_mfma_f32_16x16x32_bf16 v[18:21], v[200:203], v[162:165], v[18:21]
	v_mfma_f32_16x16x32_bf16 v[6:9], v[178:181], v[170:173], v[6:9]
	v_mfma_f32_16x16x32_bf16 v[2:5], v[200:203], v[170:173], v[2:5]
	v_mfma_f32_16x16x32_bf16 v[70:73], v[182:185], v[150:153], v[70:73]
	v_mfma_f32_16x16x32_bf16 v[58:61], v[204:207], v[150:153], v[58:61]
	v_mfma_f32_16x16x32_bf16 v[38:41], v[182:185], v[158:161], v[38:41]
	v_mfma_f32_16x16x32_bf16 v[34:37], v[204:207], v[158:161], v[34:37]
	v_mfma_f32_16x16x32_bf16 v[22:25], v[182:185], v[166:169], v[22:25]
	v_mfma_f32_16x16x32_bf16 v[18:21], v[204:207], v[166:169], v[18:21]
	v_mfma_f32_16x16x32_bf16 v[6:9], v[182:185], v[174:177], v[6:9]
	v_mfma_f32_16x16x32_bf16 v[2:5], v[204:207], v[174:177], v[2:5]
	s_setprio 0
	s_barrier
	s_mov_b32 m0, s59
	v_lshl_add_u64 v[208:209], v[232:233], 0, s[64:65]
	ds_read_b128 v[146:149], v228 offset:49152
	ds_read_b128 v[150:153], v228 offset:50176
	ds_read_b128 v[154:157], v228 offset:51200
	ds_read_b128 v[158:161], v228 offset:52224
	ds_read_b128 v[162:165], v228 offset:53248
	ds_read_b128 v[166:169], v228 offset:54272
	ds_read_b128 v[170:173], v228 offset:55296
	ds_read_b128 v[174:177], v228 offset:56320
	global_load_lds_dwordx4 v[208:209], off
	v_lshl_add_u64 v[208:209], v[234:235], 0, s[64:65]
	s_mov_b32 m0, s44
	s_nop 0
	global_load_lds_dwordx4 v[208:209], off
	s_barrier
; #define PG8_STAGE(bufoff, gbase, voff) do { _Pragma("unroll") for (int _i = 0; _i < 2; ++_i) \
;         __builtin_amdgcn_global_load_lds((const unsigned*)((const char*)(gbase) + (voff)[_i]), (LAS unsigned*)(lds + (bufoff) + ldsw + _i * 8192), 16, 0, 0); } while (0)
; #define PG8_LDA(dst, b, h) do { _Pragma("unroll") for (int m = 0; m < 4; ++m) _Pragma("unroll") for (int k = 0; k < 2; ++k) dst[m][k] = *(const LAS bf16x8*)(lds + PG8_SA(b, h) + aoff + m * 2048 + k * 1024); } while (0)
; #define PG8_LDB(dst, b, h) do { _Pragma("unroll") for (int n = 0; n < 2; ++n) _Pragma("unroll") for (int k = 0; k < 2; ++k) dst[n][k] = *(const LAS bf16x8*)(lds + PG8_SB(b, h) + boff + n * 2048 + k * 1024); } while (0)
; #define PG8_WAIT_V(n) asm volatile("s_waitcnt vmcnt(" #n ")" ::: "memory")
; #define PG8_WAIT_L(n) asm volatile("s_waitcnt lgkmcnt(" #n ")" ::: "memory")
; #define PG8_BAR __builtin_amdgcn_s_barrier()
; #define PG8_SCHED __builtin_amdgcn_sched_barrier(0)
; template <class EpiFn>
; DI void gemm_phase(LAS unsigned char* lds, const Sched& S, const bool perm, const EpiFn& E) {
;     ...
;             PG8_LDB(B0, 0, 0); PG8_SCHED; PG8_LDA(At, 0, 0); PG8_STAGE(PG8_SA(1, 1), a1 + hstep, voffA);
;             PG8_WAIT_L(8); PG8_BAR; PG8_WAIT_L(0); PG8_MMA(0, 0, At, B0); PG8_BAR; PG8_SCHED;
;             PG8_LDB(B1, 0, 1); PG8_STAGE(PG8_SB(0, 0), b2, voffB);
;             PG8_BAR; PG8_WAIT_L(0); PG8_MMA(0, 1, At, B1); PG8_BAR;
;             PG8_LDA(At, 0, 1); PG8_STAGE(PG8_SA(0, 0), a2, voffA);
;             PG8_BAR; PG8_WAIT_L(0); PG8_MMA(1, 0, At, B0); PG8_BAR; PG8_SCHED;
;             PG8_STAGE(PG8_SB(0, 1), b2 + hstep, voffB);
;             PG8_WAIT_V(6); PG8_BAR; PG8_MMA(1, 1, At, B1); PG8_BAR;
;             PG8_LDB(B0, 1, 0); PG8_SCHED; PG8_LDA(At, 1, 0); PG8_STAGE(PG8_SA(0, 1), a2 + hstep, voffA);
;             PG8_WAIT_L(8); PG8_BAR; PG8_WAIT_L(0); PG8_MMA(0, 0, At, B0); PG8_BAR; PG8_SCHED;
;             PG8_LDB(B1, 1, 1); PG8_STAGE(PG8_SB(1, 0), b3, voffB);
;             PG8_BAR; PG8_WAIT_L(0); PG8_MMA(0, 1, At, B1); PG8_BAR;
;             PG8_LDA(At, 1, 1); PG8_STAGE(PG8_SA(1, 0), a3, voffA);
;             PG8_BAR; PG8_WAIT_L(0); PG8_MMA(1, 0, At, B0); PG8_BAR; PG8_SCHED;
;             PG8_STAGE(PG8_SB(1, 1), b3 + hstep, voffB);
;             PG8_WAIT_V(6); PG8_BAR; PG8_MMA(1, 1, At, B1); PG8_BAR;
;         }
	s_waitcnt lgkmcnt(0)
	s_setprio 1
	s_waitcnt lgkmcnt(0)
	v_mfma_f32_16x16x32_bf16 v[126:129], v[130:133], v[146:149], v[126:129]
	v_mfma_f32_16x16x32_bf16 v[122:125], v[138:141], v[146:149], v[122:125]
	v_mfma_f32_16x16x32_bf16 v[114:117], v[130:133], v[154:157], v[114:117]
	v_mfma_f32_16x16x32_bf16 v[110:113], v[138:141], v[154:157], v[110:113]
	v_mfma_f32_16x16x32_bf16 v[98:101], v[130:133], v[162:165], v[98:101]
	v_mfma_f32_16x16x32_bf16 v[90:93], v[138:141], v[162:165], v[90:93]
	v_mfma_f32_16x16x32_bf16 v[82:85], v[130:133], v[170:173], v[82:85]
	v_mfma_f32_16x16x32_bf16 v[74:77], v[138:141], v[170:173], v[74:77]
	v_mfma_f32_16x16x32_bf16 v[126:129], v[134:137], v[150:153], v[126:129]
	v_mfma_f32_16x16x32_bf16 v[122:125], v[142:145], v[150:153], v[122:125]
	v_mfma_f32_16x16x32_bf16 v[114:117], v[134:137], v[158:161], v[114:117]
	v_mfma_f32_16x16x32_bf16 v[110:113], v[142:145], v[158:161], v[110:113]
	v_mfma_f32_16x16x32_bf16 v[98:101], v[134:137], v[166:169], v[98:101]
	v_mfma_f32_16x16x32_bf16 v[90:93], v[142:145], v[166:169], v[90:93]
	v_mfma_f32_16x16x32_bf16 v[82:85], v[134:137], v[174:177], v[82:85]
	v_mfma_f32_16x16x32_bf16 v[74:77], v[142:145], v[174:177], v[74:77]
	s_setprio 0
	s_barrier
	s_add_i32 s8, s8, s75
	v_lshl_add_u64 v[130:131], v[236:237], 0, s[64:65]
	s_mov_b32 m0, s8
	s_nop 0
	global_load_lds_dwordx4 v[130:131], off
	v_lshl_add_u64 v[130:131], v[238:239], 0, s[64:65]
	s_add_i32 m0, s8, 0x2000
	s_nop 0
	global_load_lds_dwordx4 v[130:131], off
	s_waitcnt vmcnt(6)
	s_barrier
	s_setprio 1
	v_mfma_f32_16x16x32_bf16 v[102:105], v[178:181], v[146:149], v[102:105]
	v_mfma_f32_16x16x32_bf16 v[94:97], v[200:203], v[146:149], v[94:97]
	v_mfma_f32_16x16x32_bf16 v[86:89], v[178:181], v[154:157], v[86:89]
	v_mfma_f32_16x16x32_bf16 v[78:81], v[200:203], v[154:157], v[78:81]
	v_mfma_f32_16x16x32_bf16 v[66:69], v[178:181], v[162:165], v[66:69]
	v_mfma_f32_16x16x32_bf16 v[62:65], v[200:203], v[162:165], v[62:65]
	v_mfma_f32_16x16x32_bf16 v[54:57], v[178:181], v[170:173], v[54:57]
	v_mfma_f32_16x16x32_bf16 v[46:49], v[200:203], v[170:173], v[46:49]
	v_mfma_f32_16x16x32_bf16 v[102:105], v[182:185], v[150:153], v[102:105]
	v_mfma_f32_16x16x32_bf16 v[94:97], v[204:207], v[150:153], v[94:97]
	v_mfma_f32_16x16x32_bf16 v[86:89], v[182:185], v[158:161], v[86:89]
	v_mfma_f32_16x16x32_bf16 v[78:81], v[204:207], v[158:161], v[78:81]
	v_mfma_f32_16x16x32_bf16 v[66:69], v[182:185], v[166:169], v[66:69]
	v_mfma_f32_16x16x32_bf16 v[62:65], v[204:207], v[166:169], v[62:65]
	v_mfma_f32_16x16x32_bf16 v[54:57], v[182:185], v[174:177], v[54:57]
	v_mfma_f32_16x16x32_bf16 v[46:49], v[204:207], v[174:177], v[46:49]
	s_setprio 0
	s_barrier
	s_add_u32 s6, s6, 0x100
	s_addc_u32 s7, s7, 0
	s_add_u32 s18, s18, 0x100
	s_addc_u32 s51, s51, 0
	s_cmp_ge_u32 s61, s16
	s_mov_b32 s60, s61
	s_cbranch_scc1 .Lgemm_trips_done
.LBB0_395:
	s_add_i32 s61, s60, 2
	s_add_u32 s8, s6, 0x80
	s_addc_u32 s9, s7, 0
	s_add_i32 s62, 0, 0x10000
	v_add_u32_e32 v0, s62, v222
	ds_read_b128 v[130:133], v0
	ds_read_b128 v[134:137], v0 offset:1024
	ds_read_b128 v[138:141], v0 offset:2048
	ds_read_b128 v[142:145], v0 offset:3072
	s_cmp_eq_u32 s17, s60
	s_cselect_b32 s9, s13, s9
	s_cselect_b32 s8, s12, s8
	s_cselect_b32 s41, s39, s51
	s_cselect_b32 s40, s38, s18
	v_lshl_add_u64 v[178:179], s[6:7], 0, v[196:197]
	s_add_i32 m0, s26, 0xc000
	ds_read_b128 v[146:149], v228
	ds_read_b128 v[150:153], v228 offset:1024
	ds_read_b128 v[154:157], v228 offset:2048
	ds_read_b128 v[158:161], v228 offset:3072
	ds_read_b128 v[162:165], v228 offset:4096
	ds_read_b128 v[166:169], v228 offset:5120
	ds_read_b128 v[170:173], v228 offset:6144
	ds_read_b128 v[174:177], v228 offset:7168
	global_load_lds_dwordx4 v[178:179], off
	v_lshl_add_u64 v[178:179], s[6:7], 0, v[198:199]
	s_add_i32 m0, s26, 0xe000
	s_nop 0
	global_load_lds_dwordx4 v[178:179], off
	s_waitcnt lgkmcnt(8)
	s_barrier
	s_waitcnt lgkmcnt(0)
	s_setprio 1
	s_waitcnt lgkmcnt(0)
	v_mfma_f32_16x16x32_bf16 v[118:121], v[130:133], v[146:149], v[118:121]
	v_mfma_f32_16x16x32_bf16 v[106:109], v[138:141], v[146:149], v[106:109]
	v_mfma_f32_16x16x32_bf16 v[50:53], v[130:133], v[154:157], v[50:53]
	v_mfma_f32_16x16x32_bf16 v[42:45], v[138:141], v[154:157], v[42:45]
	v_mfma_f32_16x16x32_bf16 v[30:33], v[130:133], v[162:165], v[30:33]
	v_mfma_f32_16x16x32_bf16 v[26:29], v[138:141], v[162:165], v[26:29]
	v_mfma_f32_16x16x32_bf16 v[14:17], v[130:133], v[170:173], v[14:17]
	v_mfma_f32_16x16x32_bf16 v[10:13], v[138:141], v[170:173], v[10:13]
	v_mfma_f32_16x16x32_bf16 v[118:121], v[134:137], v[150:153], v[118:121]
	v_mfma_f32_16x16x32_bf16 v[106:109], v[142:145], v[150:153], v[106:109]
	v_mfma_f32_16x16x32_bf16 v[50:53], v[134:137], v[158:161], v[50:53]
	v_mfma_f32_16x16x32_bf16 v[42:45], v[142:145], v[158:161], v[42:45]
	v_mfma_f32_16x16x32_bf16 v[30:33], v[134:137], v[166:169], v[30:33]
	v_mfma_f32_16x16x32_bf16 v[26:29], v[142:145], v[166:169], v[26:29]
	v_mfma_f32_16x16x32_bf16 v[14:17], v[134:137], v[174:177], v[14:17]
	v_mfma_f32_16x16x32_bf16 v[10:13], v[142:145], v[174:177], v[10:13]
	s_setprio 0
	s_barrier
	s_add_i32 s60, 0, 0x14000
	s_add_i32 s62, s62, s75
	v_add_u32_e32 v0, s60, v222
	v_lshl_add_u64 v[208:209], s[40:41], 0, v[192:193]
	s_mov_b32 m0, s62
	ds_read_b128 v[178:181], v0
	ds_read_b128 v[182:185], v0 offset:1024
	ds_read_b128 v[200:203], v0 offset:2048
	ds_read_b128 v[204:207], v0 offset:3072
	global_load_lds_dwordx4 v[208:209], off
	v_lshl_add_u64 v[230:231], s[40:41], 0, v[188:189]
	s_add_i32 m0, s62, 0x2000
	s_nop 0
	global_load_lds_dwordx4 v[230:231], off
	s_barrier
; #define PG8_STAGE(bufoff, gbase, voff) do { _Pragma("unroll") for (int _i = 0; _i < 2; ++_i) \
;         __builtin_amdgcn_global_load_lds((const unsigned*)((const char*)(gbase) + (voff)[_i]), (LAS unsigned*)(lds + (bufoff) + ldsw + _i * 8192), 16, 0, 0); } while (0)
; #define PG8_LDA(dst, b, h) do { _Pragma("unroll") for (int m = 0; m < 4; ++m) _Pragma("unroll") for (int k = 0; k < 2; ++k) dst[m][k] = *(const LAS bf16x8*)(lds + PG8_SA(b, h) + aoff + m * 2048 + k * 1024); } while (0)
; #define PG8_LDB(dst, b, h) do { _Pragma("unroll") for (int n = 0; n < 2; ++n) _Pragma("unroll") for (int k = 0; k < 2; ++k) dst[n][k] = *(const LAS bf16x8*)(lds + PG8_SB(b, h) + boff + n * 2048 + k * 1024); } while (0)
; #define PG8_MMA(ai, bj, At, Bt) do { __builtin_amdgcn_s_setprio(1); _Pragma("unroll") for (int m = 0; m < 4; ++m) _Pragma("unroll") for (int n = 0; n < 2; ++n) _Pragma("unroll") for (int k = 0; k < 2; ++k) \
;         acc[ai][bj][m][n] = __builtin_amdgcn_mfma_f32_16x16x32_bf16(Bt[n][k], At[m][k], acc[ai][bj][m][n], 0, 0, 0); __builtin_amdgcn_s_setprio(0); } while (0)
; #define PG8_WAIT_V(n) asm volatile("s_waitcnt vmcnt(" #n ")" ::: "memory")
; #define PG8_WAIT_L(n) asm volatile("s_waitcnt lgkmcnt(" #n ")" ::: "memory")
; #define PG8_BAR __builtin_amdgcn_s_barrier()
; #define PG8_SCHED __builtin_amdgcn_sched_barrier(0)
; template <class EpiFn>
; DI void gemm_phase(LAS unsigned char* lds, const Sched& S, const bool perm, const EpiFn& E) {
;     ...
;             PG8_BAR; PG8_WAIT_L(0); PG8_MMA(0, 1, At, B1); PG8_BAR;
;             PG8_LDA(At, 0, 1); PG8_STAGE(PG8_SA(0, 0), a2, voffA);
;             PG8_BAR; PG8_WAIT_L(0); PG8_MMA(1, 0, At, B0); PG8_BAR; PG8_SCHED;
;             PG8_STAGE(PG8_SB(0, 1), b2 + hstep, voffB);
;             PG8_WAIT_V(6); PG8_BAR; PG8_MMA(1, 1, At, B1); PG8_BAR;
;             PG8_LDB(B0, 1, 0); PG8_SCHED; PG8_LDA(At, 1, 0); PG8_STAGE(PG8_SA(0, 1), a2 + hstep, voffA);
;             PG8_WAIT_L(8); PG8_BAR; PG8_WAIT_L(0); PG8_MMA(0, 0, At, B0); PG8_BAR; PG8_SCHED;
	s_waitcnt lgkmcnt(0)
	s_setprio 1
	s_waitcnt lgkmcnt(0)
	v_mfma_f32_16x16x32_bf16 v[70:73], v[178:181], v[146:149], v[70:73]
	v_mfma_f32_16x16x32_bf16 v[58:61], v[200:203], v[146:149], v[58:61]
	v_mfma_f32_16x16x32_bf16 v[38:41], v[178:181], v[154:157], v[38:41]
	v_mfma_f32_16x16x32_bf16 v[34:37], v[200:203], v[154:157], v[34:37]
	v_mfma_f32_16x16x32_bf16 v[22:25], v[178:181], v[162:165], v[22:25]
	v_mfma_f32_16x16x32_bf16 v[18:21], v[200:203], v[162:165], v[18:21]
	v_mfma_f32_16x16x32_bf16 v[6:9], v[178:181], v[170:173], v[6:9]
	v_mfma_f32_16x16x32_bf16 v[2:5], v[200:203], v[170:173], v[2:5]
	v_mfma_f32_16x16x32_bf16 v[70:73], v[182:185], v[150:153], v[70:73]
	v_mfma_f32_16x16x32_bf16 v[58:61], v[204:207], v[150:153], v[58:61]
	v_mfma_f32_16x16x32_bf16 v[38:41], v[182:185], v[158:161], v[38:41]
	v_mfma_f32_16x16x32_bf16 v[34:37], v[204:207], v[158:161], v[34:37]
	v_mfma_f32_16x16x32_bf16 v[22:25], v[182:185], v[166:169], v[22:25]
	v_mfma_f32_16x16x32_bf16 v[18:21], v[204:207], v[166:169], v[18:21]
	v_mfma_f32_16x16x32_bf16 v[6:9], v[182:185], v[174:177], v[6:9]
	v_mfma_f32_16x16x32_bf16 v[2:5], v[204:207], v[174:177], v[2:5]
	s_setprio 0
	s_barrier
	s_mov_b32 m0, s26
	v_lshl_add_u64 v[232:233], s[8:9], 0, v[190:191]
	ds_read_b128 v[146:149], v228 offset:16384
	ds_read_b128 v[150:153], v228 offset:17408
	ds_read_b128 v[154:157], v228 offset:18432
	ds_read_b128 v[158:161], v228 offset:19456
	ds_read_b128 v[162:165], v228 offset:20480
	ds_read_b128 v[166:169], v228 offset:21504
	ds_read_b128 v[170:173], v228 offset:22528
	ds_read_b128 v[174:177], v228 offset:23552
	global_load_lds_dwordx4 v[232:233], off
	v_lshl_add_u64 v[234:235], s[8:9], 0, v[186:187]
	s_mov_b32 m0, s57
	s_nop 0
	global_load_lds_dwordx4 v[234:235], off
	s_barrier
	s_waitcnt lgkmcnt(0)
	s_setprio 1
	s_waitcnt lgkmcnt(0)
	v_mfma_f32_16x16x32_bf16 v[126:129], v[130:133], v[146:149], v[126:129]
	v_mfma_f32_16x16x32_bf16 v[122:125], v[138:141], v[146:149], v[122:125]
	v_mfma_f32_16x16x32_bf16 v[114:117], v[130:133], v[154:157], v[114:117]
	v_mfma_f32_16x16x32_bf16 v[110:113], v[138:141], v[154:157], v[110:113]
	v_mfma_f32_16x16x32_bf16 v[98:101], v[130:133], v[162:165], v[98:101]
	v_mfma_f32_16x16x32_bf16 v[90:93], v[138:141], v[162:165], v[90:93]
	v_mfma_f32_16x16x32_bf16 v[82:85], v[130:133], v[170:173], v[82:85]
	v_mfma_f32_16x16x32_bf16 v[74:77], v[138:141], v[170:173], v[74:77]
	v_mfma_f32_16x16x32_bf16 v[126:129], v[134:137], v[150:153], v[126:129]
	v_mfma_f32_16x16x32_bf16 v[122:125], v[142:145], v[150:153], v[122:125]
	v_mfma_f32_16x16x32_bf16 v[114:117], v[134:137], v[158:161], v[114:117]
	v_mfma_f32_16x16x32_bf16 v[110:113], v[142:145], v[158:161], v[110:113]
	v_mfma_f32_16x16x32_bf16 v[98:101], v[134:137], v[166:169], v[98:101]
	v_mfma_f32_16x16x32_bf16 v[90:93], v[142:145], v[166:169], v[90:93]
	v_mfma_f32_16x16x32_bf16 v[82:85], v[134:137], v[174:177], v[82:85]
	v_mfma_f32_16x16x32_bf16 v[74:77], v[142:145], v[174:177], v[74:77]
	s_setprio 0
	s_barrier
	s_add_u32 s40, s40, s92
	s_addc_u32 s41, s41, s93
	s_add_i32 s60, s60, s75
	v_lshl_add_u64 v[236:237], s[40:41], 0, v[192:193]
	s_mov_b32 m0, s60
	v_lshl_add_u64 v[238:239], s[40:41], 0, v[188:189]
	global_load_lds_dwordx4 v[236:237], off
	s_add_i32 m0, s60, 0x2000
	s_nop 0
	global_load_lds_dwordx4 v[238:239], off
	s_waitcnt vmcnt(6)
	s_barrier
	s_setprio 1
	v_mfma_f32_16x16x32_bf16 v[102:105], v[178:181], v[146:149], v[102:105]
	v_mfma_f32_16x16x32_bf16 v[94:97], v[200:203], v[146:149], v[94:97]
	v_mfma_f32_16x16x32_bf16 v[86:89], v[178:181], v[154:157], v[86:89]
	v_mfma_f32_16x16x32_bf16 v[78:81], v[200:203], v[154:157], v[78:81]
	v_mfma_f32_16x16x32_bf16 v[66:69], v[178:181], v[162:165], v[66:69]
	v_mfma_f32_16x16x32_bf16 v[62:65], v[200:203], v[162:165], v[62:65]
	v_mfma_f32_16x16x32_bf16 v[54:57], v[178:181], v[170:173], v[54:57]
	v_mfma_f32_16x16x32_bf16 v[46:49], v[200:203], v[170:173], v[46:49]
	v_mfma_f32_16x16x32_bf16 v[102:105], v[182:185], v[150:153], v[102:105]
	v_mfma_f32_16x16x32_bf16 v[94:97], v[204:207], v[150:153], v[94:97]
	v_mfma_f32_16x16x32_bf16 v[86:89], v[182:185], v[158:161], v[86:89]
	v_mfma_f32_16x16x32_bf16 v[78:81], v[204:207], v[158:161], v[78:81]
	v_mfma_f32_16x16x32_bf16 v[66:69], v[182:185], v[166:169], v[66:69]
	v_mfma_f32_16x16x32_bf16 v[62:65], v[204:207], v[166:169], v[62:65]
	v_mfma_f32_16x16x32_bf16 v[54:57], v[182:185], v[174:177], v[54:57]
	v_mfma_f32_16x16x32_bf16 v[46:49], v[204:207], v[174:177], v[46:49]
	s_setprio 0
	s_barrier
	s_add_i32 s40, 0, 0x18000
	v_add_u32_e32 v0, s40, v222
	ds_read_b128 v[130:133], v0
	ds_read_b128 v[134:137], v0 offset:1024
	ds_read_b128 v[138:141], v0 offset:2048
	ds_read_b128 v[142:145], v0 offset:3072
	s_add_u32 s8, s8, s92
	s_addc_u32 s9, s9, s93
	s_mov_b32 m0, s54
	v_lshl_add_u64 v[178:179], s[8:9], 0, v[190:191]
	ds_read_b128 v[146:149], v228 offset:32768
	ds_read_b128 v[150:153], v228 offset:33792
	ds_read_b128 v[154:157], v228 offset:34816
	ds_read_b128 v[158:161], v228 offset:35840
	ds_read_b128 v[162:165], v228 offset:36864
	ds_read_b128 v[166:169], v228 offset:37888
	ds_read_b128 v[170:173], v228 offset:38912
	ds_read_b128 v[174:177], v228 offset:39936
	global_load_lds_dwordx4 v[178:179], off
	v_lshl_add_u64 v[178:179], s[8:9], 0, v[186:187]
	s_mov_b32 m0, s33
	s_nop 0
	global_load_lds_dwordx4 v[178:179], off
	s_waitcnt lgkmcnt(8)
	s_barrier
; #define PG8_STAGE(bufoff, gbase, voff) do { _Pragma("unroll") for (int _i = 0; _i < 2; ++_i) \
;         __builtin_amdgcn_global_load_lds((const unsigned*)((const char*)(gbase) + (voff)[_i]), (LAS unsigned*)(lds + (bufoff) + ldsw + _i * 8192), 16, 0, 0); } while (0)
; #define PG8_LDA(dst, b, h) do { _Pragma("unroll") for (int m = 0; m < 4; ++m) _Pragma("unroll") for (int k = 0; k < 2; ++k) dst[m][k] = *(const LAS bf16x8*)(lds + PG8_SA(b, h) + aoff + m * 2048 + k * 1024); } while (0)
; #define PG8_LDB(dst, b, h) do { _Pragma("unroll") for (int n = 0; n < 2; ++n) _Pragma("unroll") for (int k = 0; k < 2; ++k) dst[n][k] = *(const LAS bf16x8*)(lds + PG8_SB(b, h) + boff + n * 2048 + k * 1024); } while (0)
; #define PG8_MMA(ai, bj, At, Bt) do { __builtin_amdgcn_s_setprio(1); _Pragma("unroll") for (int m = 0; m < 4; ++m) _Pragma("unroll") for (int n = 0; n < 2; ++n) _Pragma("unroll") for (int k = 0; k < 2; ++k) \
;         acc[ai][bj][m][n] = __builtin_amdgcn_mfma_f32_16x16x32_bf16(Bt[n][k], At[m][k], acc[ai][bj][m][n], 0, 0, 0); __builtin_amdgcn_s_setprio(0); } while (0)
; #define PG8_WAIT_V(n) asm volatile("s_waitcnt vmcnt(" #n ")" ::: "memory")
; #define PG8_WAIT_L(n) asm volatile("s_waitcnt lgkmcnt(" #n ")" ::: "memory")
; #define PG8_BAR __builtin_amdgcn_s_barrier()
; #define PG8_SCHED __builtin_amdgcn_sched_barrier(0)
; template <class EpiFn>
; DI void gemm_phase(LAS unsigned char* lds, const Sched& S, const bool perm, const EpiFn& E) {
;     ...
;             PG8_WAIT_L(8); PG8_BAR; PG8_WAIT_L(0); PG8_MMA(0, 0, At, B0); PG8_BAR; PG8_SCHED;
;             PG8_LDB(B1, 1, 1); PG8_STAGE(PG8_SB(1, 0), b3, voffB);
;             PG8_BAR; PG8_WAIT_L(0); PG8_MMA(0, 1, At, B1); PG8_BAR;
;             PG8_LDA(At, 1, 1); PG8_STAGE(PG8_SA(1, 0), a3, voffA);
;             PG8_BAR; PG8_WAIT_L(0); PG8_MMA(1, 0, At, B0); PG8_BAR; PG8_SCHED;
;             PG8_STAGE(PG8_SB(1, 1), b3 + hstep, voffB);
;             PG8_WAIT_V(6); PG8_BAR; PG8_MMA(1, 1, At, B1); PG8_BAR;
;         }
	s_waitcnt lgkmcnt(0)
	s_setprio 1
	s_waitcnt lgkmcnt(0)
	v_mfma_f32_16x16x32_bf16 v[118:121], v[130:133], v[146:149], v[118:121]
	v_mfma_f32_16x16x32_bf16 v[106:109], v[138:141], v[146:149], v[106:109]
	v_mfma_f32_16x16x32_bf16 v[50:53], v[130:133], v[154:157], v[50:53]
	v_mfma_f32_16x16x32_bf16 v[42:45], v[138:141], v[154:157], v[42:45]
	v_mfma_f32_16x16x32_bf16 v[30:33], v[130:133], v[162:165], v[30:33]
	v_mfma_f32_16x16x32_bf16 v[26:29], v[138:141], v[162:165], v[26:29]
	v_mfma_f32_16x16x32_bf16 v[14:17], v[130:133], v[170:173], v[14:17]
	v_mfma_f32_16x16x32_bf16 v[10:13], v[138:141], v[170:173], v[10:13]
	v_mfma_f32_16x16x32_bf16 v[118:121], v[134:137], v[150:153], v[118:121]
	v_mfma_f32_16x16x32_bf16 v[106:109], v[142:145], v[150:153], v[106:109]
	v_mfma_f32_16x16x32_bf16 v[50:53], v[134:137], v[158:161], v[50:53]
	v_mfma_f32_16x16x32_bf16 v[42:45], v[142:145], v[158:161], v[42:45]
	v_mfma_f32_16x16x32_bf16 v[30:33], v[134:137], v[166:169], v[30:33]
	v_mfma_f32_16x16x32_bf16 v[26:29], v[142:145], v[166:169], v[26:29]
	v_mfma_f32_16x16x32_bf16 v[14:17], v[134:137], v[174:177], v[14:17]
	v_mfma_f32_16x16x32_bf16 v[10:13], v[142:145], v[174:177], v[10:13]
	s_setprio 0
	s_barrier
	s_add_i32 s8, 0, 0x1c000
	s_add_i32 s9, s40, s75
	v_add_u32_e32 v0, s8, v222
	v_lshl_add_u64 v[208:209], v[208:209], 0, s[64:65]
	s_mov_b32 m0, s9
	ds_read_b128 v[178:181], v0
	ds_read_b128 v[182:185], v0 offset:1024
	ds_read_b128 v[200:203], v0 offset:2048
	ds_read_b128 v[204:207], v0 offset:3072
	global_load_lds_dwordx4 v[208:209], off
	v_lshl_add_u64 v[208:209], v[230:231], 0, s[64:65]
	s_add_i32 m0, s9, 0x2000
	s_nop 0
	global_load_lds_dwordx4 v[208:209], off
	s_barrier
	s_waitcnt lgkmcnt(0)
	s_setprio 1
	s_waitcnt lgkmcnt(0)
	v_mfma_f32_16x16x32_bf16 v[70:73], v[178:181], v[146:149], v[70:73]
	v_mfma_f32_16x16x32_bf16 v[58:61], v[200:203], v[146:149], v[58:61]
	v_mfma_f32_16x16x32_bf16 v[38:41], v[178:181], v[154:157], v[38:41]
	v_mfma_f32_16x16x32_bf16 v[34:37], v[200:203], v[154:157], v[34:37]
	v_mfma_f32_16x16x32_bf16 v[22:25], v[178:181], v[162:165], v[22:25]
	v_mfma_f32_16x16x32_bf16 v[18:21], v[200:203], v[162:165], v[18:21]
	v_mfma_f32_16x16x32_bf16 v[6:9], v[178:181], v[170:173], v[6:9]
	v_mfma_f32_16x16x32_bf16 v[2:5], v[200:203], v[170:173], v[2:5]
	v_mfma_f32_16x16x32_bf16 v[70:73], v[182:185], v[150:153], v[70:73]
	v_mfma_f32_16x16x32_bf16 v[58:61], v[204:207], v[150:153], v[58:61]
	v_mfma_f32_16x16x32_bf16 v[38:41], v[182:185], v[158:161], v[38:41]
	v_mfma_f32_16x16x32_bf16 v[34:37], v[204:207], v[158:161], v[34:37]
	v_mfma_f32_16x16x32_bf16 v[22:25], v[182:185], v[166:169], v[22:25]
	v_mfma_f32_16x16x32_bf16 v[18:21], v[204:207], v[166:169], v[18:21]
	v_mfma_f32_16x16x32_bf16 v[6:9], v[182:185], v[174:177], v[6:9]
	v_mfma_f32_16x16x32_bf16 v[2:5], v[204:207], v[174:177], v[2:5]
	s_setprio 0
	s_barrier
	s_mov_b32 m0, s59
	v_lshl_add_u64 v[208:209], v[232:233], 0, s[64:65]
	ds_read_b128 v[146:149], v228 offset:49152
	ds_read_b128 v[150:153], v228 offset:50176
	ds_read_b128 v[154:157], v228 offset:51200
	ds_read_b128 v[158:161], v228 offset:52224
	ds_read_b128 v[162:165], v228 offset:53248
	ds_read_b128 v[166:169], v228 offset:54272
	ds_read_b128 v[170:173], v228 offset:55296
	ds_read_b128 v[174:177], v228 offset:56320
	global_load_lds_dwordx4 v[208:209], off
	v_lshl_add_u64 v[208:209], v[234:235], 0, s[64:65]
	s_mov_b32 m0, s44
	s_nop 0
	global_load_lds_dwordx4 v[208:209], off
	s_barrier
	s_waitcnt lgkmcnt(0)
	s_setprio 1
	s_waitcnt lgkmcnt(0)
	v_mfma_f32_16x16x32_bf16 v[126:129], v[130:133], v[146:149], v[126:129]
	v_mfma_f32_16x16x32_bf16 v[122:125], v[138:141], v[146:149], v[122:125]
	v_mfma_f32_16x16x32_bf16 v[114:117], v[130:133], v[154:157], v[114:117]
	v_mfma_f32_16x16x32_bf16 v[110:113], v[138:141], v[154:157], v[110:113]
	v_mfma_f32_16x16x32_bf16 v[98:101], v[130:133], v[162:165], v[98:101]
	v_mfma_f32_16x16x32_bf16 v[90:93], v[138:141], v[162:165], v[90:93]
	v_mfma_f32_16x16x32_bf16 v[82:85], v[130:133], v[170:173], v[82:85]
	v_mfma_f32_16x16x32_bf16 v[74:77], v[138:141], v[170:173], v[74:77]
	v_mfma_f32_16x16x32_bf16 v[126:129], v[134:137], v[150:153], v[126:129]
	v_mfma_f32_16x16x32_bf16 v[122:125], v[142:145], v[150:153], v[122:125]
	v_mfma_f32_16x16x32_bf16 v[114:117], v[134:137], v[158:161], v[114:117]
	v_mfma_f32_16x16x32_bf16 v[110:113], v[142:145], v[158:161], v[110:113]
	v_mfma_f32_16x16x32_bf16 v[98:101], v[134:137], v[166:169], v[98:101]
	v_mfma_f32_16x16x32_bf16 v[90:93], v[142:145], v[166:169], v[90:93]
	v_mfma_f32_16x16x32_bf16 v[82:85], v[134:137], v[174:177], v[82:85]
	v_mfma_f32_16x16x32_bf16 v[74:77], v[142:145], v[174:177], v[74:77]
	s_setprio 0
	s_barrier
	s_add_i32 s8, s8, s75
	v_lshl_add_u64 v[130:131], v[236:237], 0, s[64:65]
	s_mov_b32 m0, s8
	s_nop 0
	global_load_lds_dwordx4 v[130:131], off
	v_lshl_add_u64 v[130:131], v[238:239], 0, s[64:65]
	s_add_i32 m0, s8, 0x2000
	s_nop 0
	global_load_lds_dwordx4 v[130:131], off
	s_waitcnt vmcnt(6)
	s_barrier
	s_setprio 1
	v_mfma_f32_16x16x32_bf16 v[102:105], v[178:181], v[146:149], v[102:105]
	v_mfma_f32_16x16x32_bf16 v[94:97], v[200:203], v[146:149], v[94:97]
	v_mfma_f32_16x16x32_bf16 v[86:89], v[178:181], v[154:157], v[86:89]
	v_mfma_f32_16x16x32_bf16 v[78:81], v[200:203], v[154:157], v[78:81]
	v_mfma_f32_16x16x32_bf16 v[66:69], v[178:181], v[162:165], v[66:69]
	v_mfma_f32_16x16x32_bf16 v[62:65], v[200:203], v[162:165], v[62:65]
	v_mfma_f32_16x16x32_bf16 v[54:57], v[178:181], v[170:173], v[54:57]
	v_mfma_f32_16x16x32_bf16 v[46:49], v[200:203], v[170:173], v[46:49]
	v_mfma_f32_16x16x32_bf16 v[102:105], v[182:185], v[150:153], v[102:105]
	v_mfma_f32_16x16x32_bf16 v[94:97], v[204:207], v[150:153], v[94:97]
	v_mfma_f32_16x16x32_bf16 v[86:89], v[182:185], v[158:161], v[86:89]
	v_mfma_f32_16x16x32_bf16 v[78:81], v[204:207], v[158:161], v[78:81]
	v_mfma_f32_16x16x32_bf16 v[66:69], v[182:185], v[166:169], v[66:69]
	v_mfma_f32_16x16x32_bf16 v[62:65], v[204:207], v[166:169], v[62:65]
	v_mfma_f32_16x16x32_bf16 v[54:57], v[182:185], v[174:177], v[54:57]
	v_mfma_f32_16x16x32_bf16 v[46:49], v[204:207], v[174:177], v[46:49]
	s_setprio 0
	s_barrier
	s_add_u32 s6, s6, 0x100
	s_addc_u32 s7, s7, 0
	s_add_u32 s18, s18, 0x100
	s_addc_u32 s51, s51, 0
	s_cmp_ge_u32 s61, s16
	s_mov_b32 s60, s61
	s_cbranch_scc0 .LBB0_395
